# weight-conversion rebalance: 1024 layer-1 items moved from P0 to the idle tail of L0 in-proj GEMM-path WGs (on v21)
# speedup vs baseline: 1.0143x; 1.0026x over previous
.LBB0_6:
	s_or_b64 exec, exec, s[6:7]
	s_mov_b64 s[22:23], s[0:1]
	v_mov_b32_e32 v3, v224
	s_load_dwordx2 s[18:19], s[22:23], 0xa0
	s_lshl_b32 s33, s24, 3
	v_readfirstlane_b32 s3, v3
	s_ashr_i32 s42, s3, 6
	s_lshl_b32 s3, s77, 3
	s_add_i32 s20, s42, s3
	s_cmpk_lg_i32 s24, 0x100
	v_writelane_b32 v252, s3, 0
	s_cselect_b64 s[6:7], -1, 0
	s_cmpk_eq_i32 s24, 0x100
	s_movk_i32 s3, 0x1f40
	s_cselect_b32 s3, s3, 0x2f00
	v_writelane_b32 v252, s6, 1
	s_cmp_lt_i32 s20, s3
	v_and_b32_e32 v1, 63, v3
	v_writelane_b32 v252, s7, 2
	s_cbranch_scc0 .LBB0_97
	s_mul_hi_i32 s6, s20, 0xae4c415d
	s_add_i32 s6, s6, s20
	s_lshr_b32 s7, s6, 31
	s_ashr_i32 s6, s6, 12
	s_add_i32 s6, s6, s7
	s_mul_i32 s7, s6, 0x1780
	s_sub_i32 s27, s20, s7
	s_waitcnt lgkmcnt(0)
	s_add_u32 s21, s18, 0x100000
	s_addc_u32 s54, s19, 0
	s_mul_i32 s26, s6, 0x1780000
	s_mul_hi_i32 s7, s6, 0x1780000
	s_add_u32 s36, s21, s26
	s_addc_u32 s37, s54, s7
	s_lshl_b32 s34, s6, 10
	s_load_dwordx4 s[8:11], s[22:23], 0x8
	s_load_dwordx4 s[12:15], s[22:23], 0x60
	s_load_dwordx2 s[28:29], s[22:23], 0x70
	s_load_dwordx2 s[30:31], s[22:23], 0x88
	s_ashr_i32 s35, s34, 31
	s_lshl_b64 s[34:35], s[34:35], 2
	s_waitcnt lgkmcnt(0)
	s_add_u32 s38, s8, s34
	s_addc_u32 s39, s9, s35
	s_mul_i32 s26, s6, 0xa00000
	s_mul_hi_i32 s7, s6, 0xa00000
	s_add_u32 s43, s10, s26
	s_addc_u32 s44, s11, s7
	s_cmpk_lt_i32 s27, 0x500
	s_mov_b32 s26, 1
	s_cbranch_scc1 .LBB0_11
	s_ashr_i32 s7, s6, 31
	s_lshl_b64 s[38:39], s[6:7], 22
	s_add_u32 s43, s12, s38
	s_addc_u32 s44, s13, s39
	s_add_u32 s40, s36, 0x500000
	s_addc_u32 s41, s37, 0
	s_cmpk_lt_u32 s27, 0x700
	s_cbranch_scc1 .LBB0_12
	s_cmpk_lt_u32 s27, 0x1200
	s_mul_i32 s26, s6, 0xb00000
	s_cselect_b64 s[40:41], -1, 0
	s_mul_hi_i32 s7, s6, 0xb00000
	s_add_u32 s26, s30, s26
	s_addc_u32 s38, s31, s7
	s_mul_hi_i32 s7, s6, 0x1600000
	s_mul_i32 s6, s6, 0x1600000
	s_add_u32 s39, s28, s6
	s_addc_u32 s43, s29, s7
	s_add_u32 s34, s14, s34
	s_addc_u32 s35, s15, s35
	s_and_b64 s[6:7], s[40:41], exec
	s_mov_b32 s6, 0x700000
	s_cselect_b32 s6, s6, 0x1200000
	s_cselect_b32 s44, s43, s38
	s_cselect_b32 s43, s39, s26
	s_cselect_b32 s39, s35, 0
	s_cselect_b32 s38, s34, 0
	s_add_u32 s36, s36, s6
	s_addc_u32 s37, s37, 0
	s_and_b64 s[6:7], s[40:41], exec
	s_movk_i32 s7, 0xf900
	s_movk_i32 s26, 0x400
	s_movk_i32 s6, 0x1600
	s_cselect_b32 s7, s7, 0xffffee00
	s_cselect_b32 s55, s26, 0xb00
	s_cselect_b32 s6, s6, 0x400
	s_cselect_b32 s26, 2, 0
	s_add_i32 s27, s27, s7
	s_branch .LBB0_13

.LBB0_295:
	s_cmpk_lt_i32 s64, 0x80
	s_cselect_b64 s[8:9], -1, 0
	s_and_b64 s[8:9], s[40:41], s[8:9]
	s_andn2_b64 vcc, exec, s[8:9]
	s_cbranch_vccnz .LBB0_391
	v_mov_b32_e32 v1, v224
	s_nop 0
	v_readfirstlane_b32 s8, v1
	s_ashr_i32 s54, s8, 6
	s_lshl_b32 s8, s64, 3
	s_add_i32 s8, s8, s54
	s_add_i32 s67, s8, 0x1f40
	s_cmpk_gt_i32 s67, 0x233f
	s_cbranch_scc1 .LBB0_391
	s_mul_hi_i32 s8, s67, 0xae4c415d
	s_add_i32 s8, s8, s67
	s_load_dwordx4 s[12:15], s[36:37], 0x8
	s_load_dwordx4 s[16:19], s[36:37], 0x60
	s_load_dwordx2 s[10:11], s[36:37], 0x70
	s_load_dwordx2 s[42:43], s[36:37], 0x88
	s_lshr_b32 s9, s8, 31
	s_ashr_i32 s8, s8, 12
	s_add_i32 s50, s8, s9
	s_mul_i32 s8, s50, 0x1780
	s_sub_i32 s55, s67, s8
	s_ashr_i32 s51, s50, 31
	s_mul_i32 s9, s50, 0x1780000
	s_mul_hi_i32 s8, s50, 0x1780000
	s_add_u32 s46, s65, s9
	s_addc_u32 s47, s66, s8
	s_cmpk_gt_i32 s55, 0x4ff
	s_cbranch_scc0 .LBB0_302
	s_cmpk_gt_u32 s55, 0x6ff
	s_cbranch_scc0 .LBB0_303
	s_cmpk_gt_u32 s55, 0x11ff
	s_cbranch_scc0 .LBB0_708
	s_add_i32 s56, s55, 0xffffee00
	s_mul_i32 s8, s50, 0xb00000
	s_mul_hi_i32 s9, s50, 0xb00000
	s_waitcnt lgkmcnt(0)
	s_add_u32 s8, s42, s8
	s_addc_u32 s9, s43, s9
	s_add_u32 s44, s46, 0x1200000
	s_addc_u32 s45, s47, 0
	s_mov_b64 s[52:53], 0
	s_cbranch_execz .LBB0_709
	s_movk_i32 s68, 0xb00
	s_movk_i32 s27, 0x400
	s_mov_b32 s26, 0
	s_mov_b64 s[48:49], 0
	s_andn2_b64 vcc, exec, s[52:53]
	s_cbranch_vccz .LBB0_304
	s_branch .LBB0_305

.LBB0_309:
	s_add_i32 s8, s27, 0xfffffc00
	s_addk_i32 s67, 0x400
	s_cmpk_lt_i32 s8, 0x1f40
	s_cselect_b64 s[56:57], -1, 0
	s_cmpk_gt_i32 s8, 0x1f3f
	s_mov_b32 s58, s46
	s_mov_b32 s62, s50
	s_cbranch_scc1 .LBB0_322
	s_mul_hi_i32 s8, s27, 0xae4c415d
	s_add_i32 s8, s8, s27
	s_lshr_b32 s9, s8, 31
	s_ashr_i32 s8, s8, 12
	s_add_i32 s60, s8, s9
	s_mul_i32 s8, s60, 0xffffe880
	s_add_i32 s70, s27, s8
	s_ashr_i32 s61, s60, 31
	s_mul_i32 s9, s60, 0x1780000
	s_mul_hi_i32 s8, s60, 0x1780000
	s_add_u32 s58, s65, s9
	s_addc_u32 s59, s66, s8
	s_cmpk_gt_i32 s70, 0x4ff
	s_mov_b64 s[62:63], -1
	s_cbranch_scc0 .LBB0_319
	s_mul_i32 s8, s60, 0x1780
	s_sub_i32 s80, s67, s8
	s_cmpk_gt_u32 s70, 0x6ff
	s_cbranch_scc0 .LBB0_316
	s_cmpk_gt_u32 s70, 0x11ff
	s_mov_b64 s[54:55], -1
	s_cbranch_scc0 .LBB0_314
	s_add_i32 s79, s80, 0xffffee00
	s_mul_i32 s8, s60, 0xb00000
	s_mul_hi_i32 s9, s60, 0xb00000
	s_waitcnt lgkmcnt(0)
	s_add_u32 s8, s42, s8
	s_addc_u32 s9, s43, s9
	s_add_u32 s52, s58, 0x1200000
	s_addc_u32 s53, s59, 0
	s_mov_b64 s[54:55], 0
